# MLA LDS-DMA issue moved behind the first K reads + hazard-window fill + SWA skip of half-tiles outside the window; on the full stack
# baseline (speedup 1.0000x reference)
.Lmla_nodma:
	s_waitcnt lgkmcnt(7)
	v_mfma_f32_32x32x16_bf16 v[82:97], v[6:9], v[98:101], 0
	ds_read_b128 v[6:9], v5 offset:256
	s_waitcnt lgkmcnt(7)
	v_mfma_f32_32x32x16_bf16 v[82:97], v[10:13], v[102:105], v[82:97]
	ds_read_b128 v[10:13], v5 offset:288
	s_waitcnt lgkmcnt(7)
	v_mfma_f32_32x32x16_bf16 v[82:97], v[14:17], v[106:109], v[82:97]
	ds_read_b128 v[14:17], v5 offset:320
	s_waitcnt lgkmcnt(7)
	v_mfma_f32_32x32x16_bf16 v[82:97], v[216:219], v[110:113], v[82:97]
	ds_read_b128 v[216:219], v5 offset:352
	s_waitcnt lgkmcnt(7)
	v_mfma_f32_32x32x16_bf16 v[82:97], v[220:223], v[114:117], v[82:97]
	s_or_b32 s87, s86, 31
	s_cmp_le_u32 s87, s24
	s_waitcnt lgkmcnt(6)
	v_mfma_f32_32x32x16_bf16 v[82:97], v[224:227], v[118:121], v[82:97]
	s_waitcnt lgkmcnt(5)
	v_mfma_f32_32x32x16_bf16 v[82:97], v[228:231], v[122:125], v[82:97]
	s_waitcnt lgkmcnt(4)
	v_mfma_f32_32x32x16_bf16 v[82:97], v[232:235], v[126:129], v[82:97]
	s_waitcnt lgkmcnt(3)
	v_mfma_f32_32x32x16_bf16 v[82:97], v[6:9], v[130:133], v[82:97]
	s_waitcnt lgkmcnt(2)
	v_mfma_f32_32x32x16_bf16 v[82:97], v[10:13], v[134:137], v[82:97]
	s_waitcnt lgkmcnt(1)
	v_mfma_f32_32x32x16_bf16 v[82:97], v[14:17], v[138:141], v[82:97]
	s_waitcnt lgkmcnt(0)
	v_mfma_f32_32x32x16_bf16 v[82:97], v[216:219], v[142:145], v[82:97]
	v_or_b32_e32 v235, s51, v205
	s_movk_i32 s98, 0x140
	v_mad_u32_u24 v235, v235, s98, v4
	ds_read_b64_tr_b16 v[238:239], v235 offset:25600
	ds_read_b64_tr_b16 v[240:241], v235 offset:28160
	ds_read_b64_tr_b16 v[242:243], v235 offset:30720
	ds_read_b64_tr_b16 v[244:245], v235 offset:33280
	ds_read_b64_tr_b16 v[246:247], v235 offset:25664
	ds_read_b64_tr_b16 v[248:249], v235 offset:28224
	s_cbranch_scc1 .LBB0_1224
	v_or_b32_e32 v5, s86, v208
	v_cmp_lt_u32_e32 vcc, v5, v213
	v_or_b32_e32 v6, 2, v5
	s_nop 0
	v_cndmask_b32_e32 v83, v212, v83, vcc
	v_cmp_le_u32_e32 vcc, v5, v213
	s_nop 1
	v_cndmask_b32_e32 v82, v212, v82, vcc
	v_cmp_le_u32_e32 vcc, v6, v213
	v_or_b32_e32 v6, 3, v5
	s_nop 0
	v_cndmask_b32_e32 v84, v212, v84, vcc
	v_cmp_le_u32_e32 vcc, v6, v213
	v_or_b32_e32 v6, 8, v5
	s_nop 0
	v_cndmask_b32_e32 v85, v212, v85, vcc
	v_cmp_le_u32_e32 vcc, v6, v213
	v_or_b32_e32 v6, 9, v5
	s_nop 0
	v_cndmask_b32_e32 v86, v212, v86, vcc
	v_cmp_le_u32_e32 vcc, v6, v213
	v_or_b32_e32 v6, 10, v5
	s_nop 0
	v_cndmask_b32_e32 v87, v212, v87, vcc
	v_cmp_le_u32_e32 vcc, v6, v213
	v_or_b32_e32 v6, 11, v5
	s_nop 0
	v_cndmask_b32_e32 v88, v212, v88, vcc
	v_cmp_le_u32_e32 vcc, v6, v213
	v_or_b32_e32 v6, 16, v5
	s_nop 0
	v_cndmask_b32_e32 v89, v212, v89, vcc
	v_cmp_le_u32_e32 vcc, v6, v213
	v_or_b32_e32 v6, 17, v5
	s_nop 0
	v_cndmask_b32_e32 v90, v212, v90, vcc
	v_cmp_le_u32_e32 vcc, v6, v213
	v_or_b32_e32 v6, 18, v5
	s_nop 0
	v_cndmask_b32_e32 v91, v212, v91, vcc
	v_cmp_le_u32_e32 vcc, v6, v213
	v_or_b32_e32 v6, 19, v5
	s_nop 0
	v_cndmask_b32_e32 v92, v212, v92, vcc
	v_cmp_le_u32_e32 vcc, v6, v213
	v_or_b32_e32 v6, 24, v5
	s_nop 0
	v_cndmask_b32_e32 v93, v212, v93, vcc
	v_cmp_le_u32_e32 vcc, v6, v213
	v_or_b32_e32 v6, 25, v5
	s_nop 0
	v_cndmask_b32_e32 v94, v212, v94, vcc
	v_cmp_le_u32_e32 vcc, v6, v213
	v_or_b32_e32 v6, 26, v5
	v_or_b32_e32 v5, 27, v5
	v_cndmask_b32_e32 v95, v212, v95, vcc
	v_cmp_le_u32_e32 vcc, v6, v213
	s_nop 1
	v_cndmask_b32_e32 v96, v212, v96, vcc
	v_cmp_le_u32_e32 vcc, v5, v213
	s_nop 1
	v_cndmask_b32_e32 v97, v212, v97, vcc
